# loop-edge rotation with the DPP wait states restored (no head thinning)
# speedup vs baseline: 1.0014x; 1.0014x over previous
.LBB0_1050:
	ds_read_b128 v[14:17], v0 offset:20480
	ds_read_b128 v[10:13], v0 offset:20496
	ds_read_b128 v[6:9], v0 offset:20512
	ds_read_b128 v[2:5], v0 offset:20528
	ds_read_b128 v[54:57], v89 offset:16384
	ds_read_b128 v[26:29], v89 offset:16640
	ds_read_b128 v[78:81], v89 offset:4096
	ds_read_b128 v[58:61], v89 offset:4352
	ds_read_b128 v[30:33], v89 offset:4608
	ds_read_b128 v[22:25], v90 offset:8704
	ds_read_b128 v[18:21], v89 offset:16896
	v_pk_mul_f32 v[66:67], v[74:75], v[108:109]
	s_waitcnt lgkmcnt(4)
	v_pk_mul_f32 v[78:79], v[14:15], v[78:79] op_sel_hi:[0,1]
	v_pk_fma_f32 v[66:67], v[76:77], v[110:111], v[66:67]
	v_pk_mul_f32 v[80:81], v[14:15], v[80:81] op_sel_hi:[0,1]
	v_add_f32_e32 v66, v66, v67
	v_pk_fma_f32 v[62:63], v[74:75], v[100:101], v[78:79]
	v_pk_fma_f32 v[64:65], v[76:77], v[102:103], v[80:81]
	v_add_f32_dpp v66, v66, v66 quad_perm:[1,0,3,2] row_mask:0xf bank_mask:0xf bound_ctrl:1
	v_mov_b32_e32 v0, v17
	v_mov_b32_e32 v82, v13
	v_add_f32_dpp v66, v66, v66 quad_perm:[2,3,0,1] row_mask:0xf bank_mask:0xf bound_ctrl:1
	v_mov_b32_e32 v84, v9
	v_mov_b32_e32 v86, v5
	v_add_f32_dpp v66, v66, v66 row_half_mirror row_mask:0xf bank_mask:0xf bound_ctrl:1
	s_add_i32 s26, s26, 1
	s_nop 0
	v_add_f32_dpp v66, v66, v66 row_ror:8 row_mask:0xf bank_mask:0xf bound_ctrl:1
	v_pk_fma_f32 v[62:63], v[120:121], v[66:67], v[62:63] op_sel_hi:[1,0,1] neg_lo:[1,0,0] neg_hi:[1,0,0]
	v_pk_fma_f32 v[64:65], v[122:123], v[66:67], v[64:65] op_sel_hi:[1,0,1] neg_lo:[1,0,0] neg_hi:[1,0,0]
	v_pk_mul_f32 v[50:51], v[112:113], v[62:63]
	v_pk_mul_f32 v[46:47], v[104:105], v[62:63]
	v_pk_fma_f32 v[50:51], v[114:115], v[64:65], v[50:51]
	s_waitcnt lgkmcnt(3)
	v_pk_fma_f32 v[66:67], v[14:15], v[58:59], v[46:47] op_sel:[1,0,0]
	v_add_f32_e32 v47, v50, v51
	v_pk_mul_f32 v[48:49], v[106:107], v[64:65]
	v_pk_mul_f32 v[56:57], v[56:57], v[64:65]
	v_add_f32_dpp v68, v47, v47 quad_perm:[1,0,3,2] row_mask:0xf bank_mask:0xf bound_ctrl:1
	v_pk_fma_f32 v[14:15], v[14:15], v[60:61], v[48:49] op_sel:[1,0,0]
	v_pk_fma_f32 v[54:55], v[54:55], v[62:63], v[56:57]
	v_add_f32_dpp v68, v68, v68 quad_perm:[2,3,0,1] row_mask:0xf bank_mask:0xf bound_ctrl:1
	v_add_f32_e32 v92, v54, v55
	s_nop 0
	v_add_f32_dpp v68, v68, v68 row_half_mirror row_mask:0xf bank_mask:0xf bound_ctrl:1
	ds_read_b128 v[46:49], v90 offset:768
	ds_read_b128 v[50:53], v89 offset:4864
	ds_read_b128 v[54:57], v90 offset:4864
	ds_read_b128 v[58:61], v90 offset:8960
	ds_read_b128 v[62:65], v89 offset:17152
	v_add_f32_dpp v68, v68, v68 row_ror:8 row_mask:0xf bank_mask:0xf bound_ctrl:1
	v_pk_fma_f32 v[42:43], v[128:129], v[68:69], v[66:67] op_sel_hi:[1,0,1] neg_lo:[1,0,0] neg_hi:[1,0,0]
	v_pk_fma_f32 v[14:15], v[130:131], v[68:69], v[14:15] op_sel_hi:[1,0,1] neg_lo:[1,0,0] neg_hi:[1,0,0]
	v_pk_mul_f32 v[38:39], v[124:125], v[42:43]
	v_pk_mul_f32 v[28:29], v[28:29], v[14:15]
	v_pk_mul_f32 v[36:37], v[118:119], v[14:15]
	v_pk_fma_f32 v[14:15], v[126:127], v[14:15], v[38:39]
	v_pk_mul_f32 v[34:35], v[116:117], v[42:43]
	v_add_f32_e32 v14, v14, v15
	v_pk_fma_f32 v[26:27], v[26:27], v[42:43], v[28:29]
	s_waitcnt lgkmcnt(7)
	v_pk_fma_f32 v[42:43], v[16:17], v[30:31], v[34:35] op_sel_hi:[0,1,1]
	v_add_f32_dpp v66, v14, v14 quad_perm:[1,0,3,2] row_mask:0xf bank_mask:0xf bound_ctrl:1
	v_pk_fma_f32 v[44:45], v[16:17], v[32:33], v[36:37] op_sel_hi:[0,1,1]
	v_add_f32_e32 v93, v26, v27
	v_add_f32_dpp v66, v66, v66 quad_perm:[2,3,0,1] row_mask:0xf bank_mask:0xf bound_ctrl:1
	ds_read_b128 v[14:17], v90 offset:1024
	ds_read_b128 v[26:29], v89 offset:5120
	ds_read_b128 v[30:33], v90 offset:5120
	ds_read_b128 v[34:37], v90 offset:9216
	ds_read_b128 v[38:41], v89 offset:17408
	v_add_f32_dpp v66, v66, v66 row_half_mirror row_mask:0xf bank_mask:0xf bound_ctrl:1
	s_nop 1
	v_add_f32_dpp v66, v66, v66 row_ror:8 row_mask:0xf bank_mask:0xf bound_ctrl:1
	s_waitcnt lgkmcnt(11)
	v_pk_fma_f32 v[22:23], v[22:23], v[66:67], v[42:43] op_sel_hi:[1,0,1] neg_lo:[1,0,0] neg_hi:[1,0,0]
	v_pk_fma_f32 v[24:25], v[24:25], v[66:67], v[44:45] op_sel_hi:[1,0,1] neg_lo:[1,0,0] neg_hi:[1,0,0]
	s_waitcnt lgkmcnt(7)
	v_pk_mul_f32 v[42:43], v[54:55], v[22:23]
	v_pk_mul_f32 v[20:21], v[20:21], v[24:25]
	v_pk_mul_f32 v[44:45], v[46:47], v[22:23]
	v_pk_mul_f32 v[46:47], v[48:49], v[24:25]
	v_pk_fma_f32 v[18:19], v[18:19], v[22:23], v[20:21]
	v_pk_fma_f32 v[20:21], v[56:57], v[24:25], v[42:43]
	v_pk_fma_f32 v[54:55], v[0:1], v[50:51], v[44:45] op_sel_hi:[0,1,1]
	v_pk_fma_f32 v[56:57], v[0:1], v[52:53], v[46:47] op_sel_hi:[0,1,1]
	v_add_f32_e32 v94, v18, v19
	v_add_f32_e32 v18, v20, v21
	s_nop 0
	s_nop 0
	v_add_f32_dpp v0, v18, v18 quad_perm:[1,0,3,2] row_mask:0xf bank_mask:0xf bound_ctrl:1
	ds_read_b128 v[18:21], v90 offset:1280
	ds_read_b128 v[22:25], v89 offset:5376
	v_add_f32_dpp v0, v0, v0 quad_perm:[2,3,0,1] row_mask:0xf bank_mask:0xf bound_ctrl:1
	ds_read_b128 v[42:45], v90 offset:5376
	ds_read_b128 v[46:49], v90 offset:9472
	v_add_f32_dpp v0, v0, v0 row_half_mirror row_mask:0xf bank_mask:0xf bound_ctrl:1
	ds_read_b128 v[50:53], v89 offset:17664
	s_nop 0
	v_add_f32_dpp v0, v0, v0 row_ror:8 row_mask:0xf bank_mask:0xf bound_ctrl:1
	s_waitcnt lgkmcnt(11)
	v_pk_fma_f32 v[54:55], v[58:59], v[0:1], v[54:55] op_sel_hi:[1,0,1] neg_lo:[1,0,0] neg_hi:[1,0,0]
	v_pk_fma_f32 v[56:57], v[60:61], v[0:1], v[56:57] op_sel_hi:[1,0,1] neg_lo:[1,0,0] neg_hi:[1,0,0]
	s_waitcnt lgkmcnt(7)
	v_pk_mul_f32 v[30:31], v[30:31], v[54:55]
	v_pk_mul_f32 v[58:59], v[64:65], v[56:57]
	v_pk_mul_f32 v[14:15], v[14:15], v[54:55]
	v_pk_fma_f32 v[54:55], v[62:63], v[54:55], v[58:59]
	v_pk_fma_f32 v[30:31], v[32:33], v[56:57], v[30:31]
	v_pk_fma_f32 v[62:63], v[10:11], v[26:27], v[14:15] op_sel_hi:[0,1,1]
	v_add_f32_e32 v95, v54, v55
	v_add_f32_e32 v14, v30, v31
	ds_write_b128 v91, v[92:95] offset:43008
	v_pk_mul_f32 v[16:17], v[16:17], v[56:57]
	v_add_f32_dpp v0, v14, v14 quad_perm:[1,0,3,2] row_mask:0xf bank_mask:0xf bound_ctrl:1
	v_pk_fma_f32 v[64:65], v[10:11], v[28:29], v[16:17] op_sel_hi:[0,1,1]
	ds_read_b128 v[14:17], v90 offset:1536
	v_add_f32_dpp v0, v0, v0 quad_perm:[2,3,0,1] row_mask:0xf bank_mask:0xf bound_ctrl:1
	ds_read_b128 v[26:29], v89 offset:5632
	ds_read_b128 v[30:33], v90 offset:5632
	v_add_f32_dpp v0, v0, v0 row_half_mirror row_mask:0xf bank_mask:0xf bound_ctrl:1
	ds_read_b128 v[54:57], v90 offset:9728
	ds_read_b128 v[58:61], v89 offset:17920
	v_add_f32_dpp v0, v0, v0 row_ror:8 row_mask:0xf bank_mask:0xf bound_ctrl:1
	s_waitcnt lgkmcnt(12)
	v_pk_fma_f32 v[34:35], v[34:35], v[0:1], v[62:63] op_sel_hi:[1,0,1] neg_lo:[1,0,0] neg_hi:[1,0,0]
	v_pk_fma_f32 v[36:37], v[36:37], v[0:1], v[64:65] op_sel_hi:[1,0,1] neg_lo:[1,0,0] neg_hi:[1,0,0]
	s_waitcnt lgkmcnt(8)
	v_pk_mul_f32 v[42:43], v[42:43], v[34:35]
	v_pk_mul_f32 v[40:41], v[40:41], v[36:37]
	v_pk_mul_f32 v[18:19], v[18:19], v[34:35]
	v_pk_mul_f32 v[20:21], v[20:21], v[36:37]
	v_pk_fma_f32 v[34:35], v[38:39], v[34:35], v[40:41]
	v_pk_fma_f32 v[36:37], v[44:45], v[36:37], v[42:43]
	v_pk_fma_f32 v[62:63], v[10:11], v[22:23], v[18:19] op_sel:[1,0,0]
	v_add_f32_e32 v18, v36, v37
	v_add_f32_e32 v96, v34, v35
	v_pk_fma_f32 v[10:11], v[10:11], v[24:25], v[20:21] op_sel:[1,0,0]
	v_add_f32_dpp v0, v18, v18 quad_perm:[1,0,3,2] row_mask:0xf bank_mask:0xf bound_ctrl:1
	ds_read_b128 v[18:21], v90 offset:1792
	ds_read_b128 v[22:25], v89 offset:5888
	v_add_f32_dpp v0, v0, v0 quad_perm:[2,3,0,1] row_mask:0xf bank_mask:0xf bound_ctrl:1
	ds_read_b128 v[34:37], v90 offset:5888
	ds_read_b128 v[38:41], v90 offset:9984
	v_add_f32_dpp v0, v0, v0 row_half_mirror row_mask:0xf bank_mask:0xf bound_ctrl:1
	ds_read_b128 v[42:45], v89 offset:18176
	s_nop 0
	v_add_f32_dpp v0, v0, v0 row_ror:8 row_mask:0xf bank_mask:0xf bound_ctrl:1
	s_waitcnt lgkmcnt(12)
	v_pk_fma_f32 v[46:47], v[46:47], v[0:1], v[62:63] op_sel_hi:[1,0,1] neg_lo:[1,0,0] neg_hi:[1,0,0]
	v_pk_fma_f32 v[10:11], v[48:49], v[0:1], v[10:11] op_sel_hi:[1,0,1] neg_lo:[1,0,0] neg_hi:[1,0,0]
	s_waitcnt lgkmcnt(7)
	v_pk_mul_f32 v[30:31], v[30:31], v[46:47]
	v_pk_mul_f32 v[48:49], v[52:53], v[10:11]
	v_pk_mul_f32 v[14:15], v[14:15], v[46:47]
	v_pk_mul_f32 v[16:17], v[16:17], v[10:11]
	v_pk_fma_f32 v[46:47], v[50:51], v[46:47], v[48:49]
	v_pk_fma_f32 v[10:11], v[32:33], v[10:11], v[30:31]
	v_add_f32_e32 v10, v10, v11
	v_add_f32_e32 v97, v46, v47
	v_pk_fma_f32 v[50:51], v[12:13], v[26:27], v[14:15] op_sel_hi:[0,1,1]
	v_add_f32_dpp v0, v10, v10 quad_perm:[1,0,3,2] row_mask:0xf bank_mask:0xf bound_ctrl:1
	v_pk_fma_f32 v[52:53], v[12:13], v[28:29], v[16:17] op_sel_hi:[0,1,1]
	ds_read_b128 v[10:13], v90 offset:2048
	v_add_f32_dpp v0, v0, v0 quad_perm:[2,3,0,1] row_mask:0xf bank_mask:0xf bound_ctrl:1
	ds_read_b128 v[14:17], v89 offset:6144
	ds_read_b128 v[26:29], v90 offset:6144
	v_add_f32_dpp v0, v0, v0 row_half_mirror row_mask:0xf bank_mask:0xf bound_ctrl:1
	ds_read_b128 v[30:33], v90 offset:10240
	ds_read_b128 v[46:49], v89 offset:18432
	v_add_f32_dpp v0, v0, v0 row_ror:8 row_mask:0xf bank_mask:0xf bound_ctrl:1
	s_waitcnt lgkmcnt(11)
	v_pk_fma_f32 v[50:51], v[54:55], v[0:1], v[50:51] op_sel_hi:[1,0,1] neg_lo:[1,0,0] neg_hi:[1,0,0]
	v_pk_fma_f32 v[52:53], v[56:57], v[0:1], v[52:53] op_sel_hi:[1,0,1] neg_lo:[1,0,0] neg_hi:[1,0,0]
	s_waitcnt lgkmcnt(7)
	v_pk_mul_f32 v[34:35], v[34:35], v[50:51]
	v_pk_mul_f32 v[54:55], v[60:61], v[52:53]
	v_pk_mul_f32 v[18:19], v[18:19], v[50:51]
	v_pk_fma_f32 v[50:51], v[58:59], v[50:51], v[54:55]
	v_pk_fma_f32 v[34:35], v[36:37], v[52:53], v[34:35]
	v_pk_fma_f32 v[58:59], v[82:83], v[22:23], v[18:19] op_sel_hi:[0,1,1]
	v_add_f32_e32 v18, v34, v35
	v_add_f32_e32 v98, v50, v51
	v_pk_mul_f32 v[20:21], v[20:21], v[52:53]
	v_add_f32_dpp v0, v18, v18 quad_perm:[1,0,3,2] row_mask:0xf bank_mask:0xf bound_ctrl:1
	v_pk_fma_f32 v[60:61], v[82:83], v[24:25], v[20:21] op_sel_hi:[0,1,1]
	ds_read_b128 v[18:21], v90 offset:2304
	v_add_f32_dpp v0, v0, v0 quad_perm:[2,3,0,1] row_mask:0xf bank_mask:0xf bound_ctrl:1
	ds_read_b128 v[22:25], v89 offset:6400
	ds_read_b128 v[34:37], v90 offset:6400
	v_add_f32_dpp v0, v0, v0 row_half_mirror row_mask:0xf bank_mask:0xf bound_ctrl:1
	ds_read_b128 v[50:53], v90 offset:10496
	ds_read_b128 v[54:57], v89 offset:18688
	v_add_f32_dpp v0, v0, v0 row_ror:8 row_mask:0xf bank_mask:0xf bound_ctrl:1
	s_waitcnt lgkmcnt(11)
	v_pk_fma_f32 v[38:39], v[38:39], v[0:1], v[58:59] op_sel_hi:[1,0,1] neg_lo:[1,0,0] neg_hi:[1,0,0]
	v_pk_fma_f32 v[40:41], v[40:41], v[0:1], v[60:61] op_sel_hi:[1,0,1] neg_lo:[1,0,0] neg_hi:[1,0,0]
	s_waitcnt lgkmcnt(7)
	v_pk_mul_f32 v[26:27], v[26:27], v[38:39]
	v_pk_mul_f32 v[44:45], v[44:45], v[40:41]
	v_pk_mul_f32 v[10:11], v[10:11], v[38:39]
	v_pk_fma_f32 v[38:39], v[42:43], v[38:39], v[44:45]
	v_pk_fma_f32 v[26:27], v[28:29], v[40:41], v[26:27]
	v_pk_fma_f32 v[58:59], v[6:7], v[14:15], v[10:11] op_sel_hi:[0,1,1]
	v_add_f32_e32 v99, v38, v39
	v_add_f32_e32 v10, v26, v27
	ds_write_b128 v91, v[96:99] offset:47104
	v_pk_mul_f32 v[12:13], v[12:13], v[40:41]
	v_add_f32_dpp v0, v10, v10 quad_perm:[1,0,3,2] row_mask:0xf bank_mask:0xf bound_ctrl:1
	v_pk_fma_f32 v[60:61], v[6:7], v[16:17], v[12:13] op_sel_hi:[0,1,1]
	ds_read_b128 v[10:13], v90 offset:2560
	v_add_f32_dpp v0, v0, v0 quad_perm:[2,3,0,1] row_mask:0xf bank_mask:0xf bound_ctrl:1
	ds_read_b128 v[14:17], v89 offset:6656
	ds_read_b128 v[26:29], v90 offset:6656
	v_add_f32_dpp v0, v0, v0 row_half_mirror row_mask:0xf bank_mask:0xf bound_ctrl:1
	ds_read_b128 v[38:41], v90 offset:10752
	ds_read_b128 v[42:45], v89 offset:18944
	v_add_f32_dpp v0, v0, v0 row_ror:8 row_mask:0xf bank_mask:0xf bound_ctrl:1
	s_waitcnt lgkmcnt(12)
	v_pk_fma_f32 v[30:31], v[30:31], v[0:1], v[58:59] op_sel_hi:[1,0,1] neg_lo:[1,0,0] neg_hi:[1,0,0]
	v_pk_fma_f32 v[32:33], v[32:33], v[0:1], v[60:61] op_sel_hi:[1,0,1] neg_lo:[1,0,0] neg_hi:[1,0,0]
	s_waitcnt lgkmcnt(8)
	v_pk_mul_f32 v[34:35], v[34:35], v[30:31]
	v_pk_mul_f32 v[48:49], v[48:49], v[32:33]
	v_pk_mul_f32 v[18:19], v[18:19], v[30:31]
	v_pk_mul_f32 v[20:21], v[20:21], v[32:33]
	v_pk_fma_f32 v[30:31], v[46:47], v[30:31], v[48:49]
	v_pk_fma_f32 v[32:33], v[36:37], v[32:33], v[34:35]
	v_pk_fma_f32 v[58:59], v[6:7], v[22:23], v[18:19] op_sel:[1,0,0]
	v_add_f32_e32 v18, v32, v33
	v_add_f32_e32 v92, v30, v31
	v_pk_fma_f32 v[6:7], v[6:7], v[24:25], v[20:21] op_sel:[1,0,0]
	v_add_f32_dpp v0, v18, v18 quad_perm:[1,0,3,2] row_mask:0xf bank_mask:0xf bound_ctrl:1
	ds_read_b128 v[18:21], v90 offset:2816
	ds_read_b128 v[22:25], v89 offset:6912
	v_add_f32_dpp v0, v0, v0 quad_perm:[2,3,0,1] row_mask:0xf bank_mask:0xf bound_ctrl:1
	ds_read_b128 v[30:33], v90 offset:6912
	ds_read_b128 v[34:37], v90 offset:11008
	v_add_f32_dpp v0, v0, v0 row_half_mirror row_mask:0xf bank_mask:0xf bound_ctrl:1
	ds_read_b128 v[46:49], v89 offset:19200
	s_nop 0
	v_add_f32_dpp v0, v0, v0 row_ror:8 row_mask:0xf bank_mask:0xf bound_ctrl:1
	s_waitcnt lgkmcnt(12)
	v_pk_fma_f32 v[50:51], v[50:51], v[0:1], v[58:59] op_sel_hi:[1,0,1] neg_lo:[1,0,0] neg_hi:[1,0,0]
	v_pk_fma_f32 v[6:7], v[52:53], v[0:1], v[6:7] op_sel_hi:[1,0,1] neg_lo:[1,0,0] neg_hi:[1,0,0]
	s_waitcnt lgkmcnt(7)
	v_pk_mul_f32 v[26:27], v[26:27], v[50:51]
	v_pk_mul_f32 v[52:53], v[56:57], v[6:7]
	v_pk_mul_f32 v[10:11], v[10:11], v[50:51]
	v_pk_mul_f32 v[12:13], v[12:13], v[6:7]
	v_pk_fma_f32 v[50:51], v[54:55], v[50:51], v[52:53]
	v_pk_fma_f32 v[6:7], v[28:29], v[6:7], v[26:27]
	v_add_f32_e32 v6, v6, v7
	v_add_f32_e32 v93, v50, v51
	v_pk_fma_f32 v[54:55], v[8:9], v[14:15], v[10:11] op_sel_hi:[0,1,1]
	v_add_f32_dpp v0, v6, v6 quad_perm:[1,0,3,2] row_mask:0xf bank_mask:0xf bound_ctrl:1
	v_pk_fma_f32 v[56:57], v[8:9], v[16:17], v[12:13] op_sel_hi:[0,1,1]
	ds_read_b128 v[6:9], v90 offset:3072
	v_add_f32_dpp v0, v0, v0 quad_perm:[2,3,0,1] row_mask:0xf bank_mask:0xf bound_ctrl:1
	ds_read_b128 v[10:13], v89 offset:7168
	ds_read_b128 v[14:17], v90 offset:7168
	v_add_f32_dpp v0, v0, v0 row_half_mirror row_mask:0xf bank_mask:0xf bound_ctrl:1
	ds_read_b128 v[26:29], v90 offset:11264
	ds_read_b128 v[50:53], v89 offset:19456
	v_add_f32_dpp v0, v0, v0 row_ror:8 row_mask:0xf bank_mask:0xf bound_ctrl:1
	s_waitcnt lgkmcnt(11)
	v_pk_fma_f32 v[38:39], v[38:39], v[0:1], v[54:55] op_sel_hi:[1,0,1] neg_lo:[1,0,0] neg_hi:[1,0,0]
	v_pk_fma_f32 v[40:41], v[40:41], v[0:1], v[56:57] op_sel_hi:[1,0,1] neg_lo:[1,0,0] neg_hi:[1,0,0]
	s_waitcnt lgkmcnt(7)
	v_pk_mul_f32 v[30:31], v[30:31], v[38:39]
	v_pk_mul_f32 v[44:45], v[44:45], v[40:41]
	v_pk_mul_f32 v[18:19], v[18:19], v[38:39]
	v_pk_fma_f32 v[38:39], v[42:43], v[38:39], v[44:45]
	v_pk_fma_f32 v[30:31], v[32:33], v[40:41], v[30:31]
	v_pk_fma_f32 v[54:55], v[84:85], v[22:23], v[18:19] op_sel_hi:[0,1,1]
	v_add_f32_e32 v18, v30, v31
	v_add_f32_e32 v94, v38, v39
	v_pk_mul_f32 v[20:21], v[20:21], v[40:41]
	v_add_f32_dpp v0, v18, v18 quad_perm:[1,0,3,2] row_mask:0xf bank_mask:0xf bound_ctrl:1
	v_pk_fma_f32 v[56:57], v[84:85], v[24:25], v[20:21] op_sel_hi:[0,1,1]
	ds_read_b128 v[18:21], v90 offset:3328
	v_add_f32_dpp v0, v0, v0 quad_perm:[2,3,0,1] row_mask:0xf bank_mask:0xf bound_ctrl:1
	ds_read_b128 v[22:25], v89 offset:7424
	ds_read_b128 v[30:33], v90 offset:7424
	v_add_f32_dpp v0, v0, v0 row_half_mirror row_mask:0xf bank_mask:0xf bound_ctrl:1
	ds_read_b128 v[38:41], v90 offset:11520
	ds_read_b128 v[42:45], v89 offset:19712
	v_add_f32_dpp v0, v0, v0 row_ror:8 row_mask:0xf bank_mask:0xf bound_ctrl:1
	s_waitcnt lgkmcnt(11)
	v_pk_fma_f32 v[34:35], v[34:35], v[0:1], v[54:55] op_sel_hi:[1,0,1] neg_lo:[1,0,0] neg_hi:[1,0,0]
	v_pk_fma_f32 v[36:37], v[36:37], v[0:1], v[56:57] op_sel_hi:[1,0,1] neg_lo:[1,0,0] neg_hi:[1,0,0]
	s_waitcnt lgkmcnt(7)
	v_pk_mul_f32 v[14:15], v[14:15], v[34:35]
	v_pk_mul_f32 v[48:49], v[48:49], v[36:37]
	v_pk_mul_f32 v[6:7], v[6:7], v[34:35]
	v_pk_fma_f32 v[34:35], v[46:47], v[34:35], v[48:49]
	v_pk_fma_f32 v[14:15], v[16:17], v[36:37], v[14:15]
	v_pk_fma_f32 v[54:55], v[2:3], v[10:11], v[6:7] op_sel_hi:[0,1,1]
	v_add_f32_e32 v95, v34, v35
	v_add_f32_e32 v6, v14, v15
	ds_write_b128 v91, v[92:95] offset:51200
	v_pk_mul_f32 v[8:9], v[8:9], v[36:37]
	v_add_f32_dpp v0, v6, v6 quad_perm:[1,0,3,2] row_mask:0xf bank_mask:0xf bound_ctrl:1
	v_pk_fma_f32 v[56:57], v[2:3], v[12:13], v[8:9] op_sel_hi:[0,1,1]
	ds_read_b128 v[6:9], v90 offset:3584
	v_add_f32_dpp v0, v0, v0 quad_perm:[2,3,0,1] row_mask:0xf bank_mask:0xf bound_ctrl:1
	ds_read_b128 v[10:13], v89 offset:7680
	ds_read_b128 v[14:17], v90 offset:7680
	v_add_f32_dpp v0, v0, v0 row_half_mirror row_mask:0xf bank_mask:0xf bound_ctrl:1
	ds_read_b128 v[34:37], v90 offset:11776
	ds_read_b128 v[46:49], v89 offset:19968
	v_add_f32_dpp v0, v0, v0 row_ror:8 row_mask:0xf bank_mask:0xf bound_ctrl:1
	s_waitcnt lgkmcnt(12)
	v_pk_fma_f32 v[26:27], v[26:27], v[0:1], v[54:55] op_sel_hi:[1,0,1] neg_lo:[1,0,0] neg_hi:[1,0,0]
	v_pk_fma_f32 v[28:29], v[28:29], v[0:1], v[56:57] op_sel_hi:[1,0,1] neg_lo:[1,0,0] neg_hi:[1,0,0]
	s_waitcnt lgkmcnt(8)
	v_pk_mul_f32 v[30:31], v[30:31], v[26:27]
	v_pk_mul_f32 v[52:53], v[52:53], v[28:29]
	v_pk_mul_f32 v[18:19], v[18:19], v[26:27]
	v_pk_mul_f32 v[20:21], v[20:21], v[28:29]
	v_pk_fma_f32 v[26:27], v[50:51], v[26:27], v[52:53]
	v_pk_fma_f32 v[28:29], v[32:33], v[28:29], v[30:31]
	v_pk_fma_f32 v[54:55], v[2:3], v[22:23], v[18:19] op_sel:[1,0,0]
	v_add_f32_e32 v18, v28, v29
	v_add_f32_e32 v96, v26, v27
	v_pk_fma_f32 v[2:3], v[2:3], v[24:25], v[20:21] op_sel:[1,0,0]
	v_add_f32_dpp v0, v18, v18 quad_perm:[1,0,3,2] row_mask:0xf bank_mask:0xf bound_ctrl:1
	ds_read_b128 v[18:21], v90 offset:3840
	ds_read_b128 v[22:25], v89 offset:7936
	v_add_f32_dpp v0, v0, v0 quad_perm:[2,3,0,1] row_mask:0xf bank_mask:0xf bound_ctrl:1
	ds_read_b128 v[26:29], v90 offset:7936
	ds_read_b128 v[30:33], v90 offset:12032
	v_add_f32_dpp v0, v0, v0 row_half_mirror row_mask:0xf bank_mask:0xf bound_ctrl:1
	ds_read_b128 v[50:53], v89 offset:20224
	s_nop 0
	v_add_f32_dpp v0, v0, v0 row_ror:8 row_mask:0xf bank_mask:0xf bound_ctrl:1
	s_waitcnt lgkmcnt(12)
	v_pk_fma_f32 v[38:39], v[38:39], v[0:1], v[54:55] op_sel_hi:[1,0,1] neg_lo:[1,0,0] neg_hi:[1,0,0]
	v_pk_fma_f32 v[2:3], v[40:41], v[0:1], v[2:3] op_sel_hi:[1,0,1] neg_lo:[1,0,0] neg_hi:[1,0,0]
	s_waitcnt lgkmcnt(7)
	v_pk_mul_f32 v[14:15], v[14:15], v[38:39]
	v_pk_mul_f32 v[40:41], v[44:45], v[2:3]
	v_pk_mul_f32 v[8:9], v[8:9], v[2:3]
	v_pk_fma_f32 v[2:3], v[16:17], v[2:3], v[14:15]
	v_pk_mul_f32 v[6:7], v[6:7], v[38:39]
	v_add_f32_e32 v0, v2, v3
	v_pk_fma_f32 v[6:7], v[4:5], v[10:11], v[6:7] op_sel_hi:[0,1,1]
	v_pk_fma_f32 v[4:5], v[4:5], v[12:13], v[8:9] op_sel_hi:[0,1,1]
	v_add_f32_dpp v0, v0, v0 quad_perm:[1,0,3,2] row_mask:0xf bank_mask:0xf bound_ctrl:1
	v_pk_fma_f32 v[38:39], v[42:43], v[38:39], v[40:41]
	ds_read_b128 v[108:111], v88 offset:4096
	v_add_f32_dpp v0, v0, v0 quad_perm:[2,3,0,1] row_mask:0xf bank_mask:0xf bound_ctrl:1
	v_add_f32_e32 v97, v38, v39
	ds_read_b128 v[100:103], v88
	v_add_f32_dpp v0, v0, v0 row_half_mirror row_mask:0xf bank_mask:0xf bound_ctrl:1
	ds_read_b128 v[120:123], v88 offset:8192
	ds_read_b128 v[112:115], v88 offset:4352
	v_add_f32_dpp v0, v0, v0 row_ror:8 row_mask:0xf bank_mask:0xf bound_ctrl:1
	s_waitcnt lgkmcnt(10)
	v_pk_fma_f32 v[2:3], v[34:35], v[0:1], v[6:7] op_sel_hi:[1,0,1] neg_lo:[1,0,0] neg_hi:[1,0,0]
	v_pk_fma_f32 v[4:5], v[36:37], v[0:1], v[4:5] op_sel_hi:[1,0,1] neg_lo:[1,0,0] neg_hi:[1,0,0]
	s_waitcnt lgkmcnt(6)
	v_pk_mul_f32 v[8:9], v[26:27], v[2:3]
	v_pk_mul_f32 v[6:7], v[48:49], v[4:5]
	v_pk_mul_f32 v[10:11], v[18:19], v[2:3]
	v_pk_mul_f32 v[12:13], v[20:21], v[4:5]
	v_pk_fma_f32 v[2:3], v[46:47], v[2:3], v[6:7]
	v_pk_fma_f32 v[4:5], v[28:29], v[4:5], v[8:9]
	v_add_f32_e32 v98, v2, v3
	v_add_f32_e32 v2, v4, v5
	v_pk_fma_f32 v[8:9], v[86:87], v[24:25], v[12:13] op_sel_hi:[0,1,1]
	s_nop 0
	v_add_f32_dpp v0, v2, v2 quad_perm:[1,0,3,2] row_mask:0xf bank_mask:0xf bound_ctrl:1
	v_pk_fma_f32 v[6:7], v[86:87], v[22:23], v[10:11] op_sel_hi:[0,1,1]
	ds_read_b128 v[104:107], v88 offset:256
	v_add_f32_dpp v0, v0, v0 quad_perm:[2,3,0,1] row_mask:0xf bank_mask:0xf bound_ctrl:1
	ds_read_b128 v[128:131], v88 offset:8448
	ds_read_b128 v[124:127], v88 offset:4608
	v_add_f32_dpp v0, v0, v0 row_half_mirror row_mask:0xf bank_mask:0xf bound_ctrl:1
	ds_read_b128 v[116:119], v88 offset:512
	s_nop 0
	v_add_f32_dpp v0, v0, v0 row_ror:8 row_mask:0xf bank_mask:0xf bound_ctrl:1
	s_waitcnt lgkmcnt(9)
	v_pk_fma_f32 v[76:77], v[32:33], v[0:1], v[8:9] op_sel_hi:[1,0,1] neg_lo:[1,0,0] neg_hi:[1,0,0]
	v_pk_fma_f32 v[74:75], v[30:31], v[0:1], v[6:7] op_sel_hi:[1,0,1] neg_lo:[1,0,0] neg_hi:[1,0,0]
	s_waitcnt lgkmcnt(8)
	v_pk_mul_f32 v[2:3], v[52:53], v[76:77]
	s_nop 0
	v_pk_fma_f32 v[2:3], v[50:51], v[74:75], v[2:3]
	s_nop 0
	v_add_f32_e32 v99, v2, v3
	ds_write_b128 v91, v[96:99] offset:55296
	s_and_b32 s2, s26, 1
	s_mul_i32 s3, s2, 0x5400
	v_lshlrev_b32_e32 v91, 2, v87
	v_lshl_add_u32 v91, s2, 14, v91
	s_add_i32 s2, s3, 0
	v_add_u32_e32 v0, s2, v85
	v_add_u32_e32 v89, s2, v83
	v_add_u32_e32 v90, s96, v83
	s_add_i32 s96, s96, 0x3000
	s_cmp_eq_u32 s96, 0x1e800
	s_cselect_b32 s96, 0x20200, s96
	s_cmp_eq_u32 s96, 0x23200
	s_cselect_b32 s96, 0x12800, s96
	v_add_u32_e32 v88, s96, v83
	s_cmpk_eq_i32 s26, 0x110
	s_waitcnt lgkmcnt(0)
	s_barrier
	s_cbranch_scc0 .LBB0_1050
	s_setprio 0
